# readout0 epilogue: all gate/x loads of 8 accumulators issued before one wait (2 batches per tile) instead of 16 serialized load-wait-store steps
# baseline (speedup 1.0000x reference)
.LBB0_536:
	s_mov_b64 s[0:1], 0x2000
	v_readlane_b32 s40, v253, 18
	v_readlane_b32 s41, v253, 19
	v_readlane_b32 s44, v253, 22
	v_readlane_b32 s45, v253, 23
	v_add_u32_e32 v211, s10, v156
	v_add_u32_e32 v186, s7, v157
	s_mov_b32 s11, s6
	s_mov_b32 s7, s21
	s_mov_b32 s10, s20
	v_readlane_b32 s42, v253, 20
	v_readlane_b32 s43, v253, 21
	v_readlane_b32 s46, v253, 24
	v_readlane_b32 s47, v253, 25
	v_readlane_b32 s48, v253, 26
	v_readlane_b32 s49, v253, 27
	v_readlane_b32 s50, v253, 28
	v_readlane_b32 s51, v253, 29
	v_readlane_b32 s52, v253, 30
	v_readlane_b32 s53, v253, 31
	v_readlane_b32 s54, v253, 32
	v_readlane_b32 s55, v253, 33
	v_ashrrev_i32_e32 v187, 31, v186
	v_lshlrev_b64 v[188:189], 2, v[186:187]
	v_mov_b32_e32 v212, s41
	v_mov_b32_e32 v213, s45
	v_mov_b32_e32 v214, s40
	v_mov_b32_e32 v215, s44
	v_mov_b32_e32 v216, s75
	v_mov_b32_e32 v217, s93
	v_mov_b32_e32 v218, s74
	v_mov_b32_e32 v219, s92
	v_mov_b32_e32 v178, v211
	v_mul_hi_i32 v179, v178, s97
	v_lshrrev_b32_e32 v180, 31, v179
	v_ashrrev_i32_e32 v179, 11, v179
	v_add_u32_e32 v179, v179, v180
	v_mul_i32_i24_e32 v180, 0x1100, v179
	v_sub_u32_e32 v180, v178, v180
	v_cmp_gt_i32_e32 vcc, s27, v180
	v_add_u32_e32 v181, s84, v179
	v_add_u32_e32 v198, 0xffffff00, v180
	v_ashrrev_i32_e32 v199, 31, v180
	v_cndmask_b32_e64 v179, v181, 8, vcc
	v_mul_hi_i32_i24_e32 v183, 0x3000, v179
	v_mul_i32_i24_e32 v182, 0x3000, v179
	v_lshl_add_u64 v[182:183], s[28:29], 0, v[182:183]
	v_lshl_add_u64 v[182:183], v[182:183], 0, s[0:1]
	v_lshl_add_u64 v[194:195], v[182:183], 0, v[188:189]
	v_cndmask_b32_e32 v185, 0, v199, vcc
	v_cndmask_b32_e32 v184, v198, v180, vcc
	v_mov_b32_e32 v182, v181
	v_ashrrev_i32_e32 v183, 31, v181
	v_cndmask_b32_e64 v198, 22, 18, vcc
	v_lshlrev_b64 v[182:183], v198, v[182:183]
	v_lshlrev_b64 v[184:185], 10, v[184:185]
	v_lshl_add_u64 v[184:185], v[184:185], 0, v[182:183]
	v_lshl_add_u64 v[184:185], v[184:185], 0, v[186:187]
	v_lshlrev_b64 v[184:185], 2, v[184:185]
	v_cndmask_b32_e32 v183, v212, v213, vcc
	v_cndmask_b32_e32 v182, v214, v215, vcc
	v_lshl_add_u64 v[196:197], v[182:183], 0, v[184:185]
	v_cndmask_b32_e32 v183, v216, v217, vcc
	v_cndmask_b32_e32 v182, v218, v219, vcc
	v_lshl_add_u64 v[190:191], v[182:183], 0, v[184:185]
	global_load_dwordx4 v[64:67], v[194:195], off
	global_load_dwordx4 v[68:71], v[196:197], off
	global_load_dwordx4 v[72:75], v[194:195], off offset:64
	global_load_dwordx4 v[76:79], v[196:197], off offset:64
	global_load_dwordx4 v[80:83], v[194:195], off offset:128
	global_load_dwordx4 v[84:87], v[196:197], off offset:128
	global_load_dwordx4 v[88:91], v[194:195], off offset:192
	global_load_dwordx4 v[92:95], v[196:197], off offset:192
	v_add_u32_e32 v178, 16, v211
	v_mul_hi_i32 v179, v178, s97
	v_lshrrev_b32_e32 v180, 31, v179
	v_ashrrev_i32_e32 v179, 11, v179
	v_add_u32_e32 v179, v179, v180
	v_mul_i32_i24_e32 v180, 0x1100, v179
	v_sub_u32_e32 v180, v178, v180
	v_cmp_gt_i32_e32 vcc, s27, v180
	v_add_u32_e32 v181, s84, v179
	v_add_u32_e32 v198, 0xffffff00, v180
	v_ashrrev_i32_e32 v199, 31, v180
	v_cndmask_b32_e64 v179, v181, 8, vcc
	v_mul_hi_i32_i24_e32 v183, 0x3000, v179
	v_mul_i32_i24_e32 v182, 0x3000, v179
	v_lshl_add_u64 v[182:183], s[28:29], 0, v[182:183]
	v_lshl_add_u64 v[182:183], v[182:183], 0, s[0:1]
	v_lshl_add_u64 v[194:195], v[182:183], 0, v[188:189]
	v_cndmask_b32_e32 v185, 0, v199, vcc
	v_cndmask_b32_e32 v184, v198, v180, vcc
	v_mov_b32_e32 v182, v181
	v_ashrrev_i32_e32 v183, 31, v181
	v_cndmask_b32_e64 v198, 22, 18, vcc
	v_lshlrev_b64 v[182:183], v198, v[182:183]
	v_lshlrev_b64 v[184:185], 10, v[184:185]
	v_lshl_add_u64 v[184:185], v[184:185], 0, v[182:183]
	v_lshl_add_u64 v[184:185], v[184:185], 0, v[186:187]
	v_lshlrev_b64 v[184:185], 2, v[184:185]
	v_cndmask_b32_e32 v183, v212, v213, vcc
	v_cndmask_b32_e32 v182, v214, v215, vcc
	v_lshl_add_u64 v[196:197], v[182:183], 0, v[184:185]
	v_cndmask_b32_e32 v183, v216, v217, vcc
	v_cndmask_b32_e32 v182, v218, v219, vcc
	v_lshl_add_u64 v[192:193], v[182:183], 0, v[184:185]
	global_load_dwordx4 v[96:99], v[194:195], off
	global_load_dwordx4 v[100:103], v[196:197], off
	global_load_dwordx4 v[104:107], v[194:195], off offset:64
	global_load_dwordx4 v[108:111], v[196:197], off offset:64
	global_load_dwordx4 v[112:115], v[194:195], off offset:128
	global_load_dwordx4 v[116:119], v[196:197], off offset:128
	global_load_dwordx4 v[120:123], v[194:195], off offset:192
	global_load_dwordx4 v[124:127], v[196:197], off offset:192
	s_waitcnt vmcnt(0)
	v_pk_fma_f32 v[62:63], v[62:63], v[66:67], v[70:71]
	v_pk_fma_f32 v[60:61], v[60:61], v[64:65], v[68:69]
	global_store_dwordx4 v[190:191], v[60:63], off
	v_pk_fma_f32 v[58:59], v[58:59], v[74:75], v[78:79]
	v_pk_fma_f32 v[56:57], v[56:57], v[72:73], v[76:77]
	global_store_dwordx4 v[190:191], v[56:59], off offset:64
	v_pk_fma_f32 v[54:55], v[54:55], v[82:83], v[86:87]
	v_pk_fma_f32 v[52:53], v[52:53], v[80:81], v[84:85]
	global_store_dwordx4 v[190:191], v[52:55], off offset:128
	v_pk_fma_f32 v[50:51], v[50:51], v[90:91], v[94:95]
	v_pk_fma_f32 v[48:49], v[48:49], v[88:89], v[92:93]
	global_store_dwordx4 v[190:191], v[48:51], off offset:192
	v_pk_fma_f32 v[46:47], v[46:47], v[98:99], v[102:103]
	v_pk_fma_f32 v[44:45], v[44:45], v[96:97], v[100:101]
	global_store_dwordx4 v[192:193], v[44:47], off
	v_pk_fma_f32 v[42:43], v[42:43], v[106:107], v[110:111]
	v_pk_fma_f32 v[40:41], v[40:41], v[104:105], v[108:109]
	global_store_dwordx4 v[192:193], v[40:43], off offset:64
	v_pk_fma_f32 v[38:39], v[38:39], v[114:115], v[118:119]
	v_pk_fma_f32 v[36:37], v[36:37], v[112:113], v[116:117]
	global_store_dwordx4 v[192:193], v[36:39], off offset:128
	v_pk_fma_f32 v[34:35], v[34:35], v[122:123], v[126:127]
	v_pk_fma_f32 v[32:33], v[32:33], v[120:121], v[124:125]
	global_store_dwordx4 v[192:193], v[32:35], off offset:192
	s_nop 1
	v_add_u32_e32 v178, 32, v211
	v_mul_hi_i32 v179, v178, s97
	v_lshrrev_b32_e32 v180, 31, v179
	v_ashrrev_i32_e32 v179, 11, v179
	v_add_u32_e32 v179, v179, v180
	v_mul_i32_i24_e32 v180, 0x1100, v179
	v_sub_u32_e32 v180, v178, v180
	v_cmp_gt_i32_e32 vcc, s27, v180
	v_add_u32_e32 v181, s84, v179
	v_add_u32_e32 v198, 0xffffff00, v180
	v_ashrrev_i32_e32 v199, 31, v180
	v_cndmask_b32_e64 v179, v181, 8, vcc
	v_mul_hi_i32_i24_e32 v183, 0x3000, v179
	v_mul_i32_i24_e32 v182, 0x3000, v179
	v_lshl_add_u64 v[182:183], s[28:29], 0, v[182:183]
	v_lshl_add_u64 v[182:183], v[182:183], 0, s[0:1]
	v_lshl_add_u64 v[194:195], v[182:183], 0, v[188:189]
	v_cndmask_b32_e32 v185, 0, v199, vcc
	v_cndmask_b32_e32 v184, v198, v180, vcc
	v_mov_b32_e32 v182, v181
	v_ashrrev_i32_e32 v183, 31, v181
	v_cndmask_b32_e64 v198, 22, 18, vcc
	v_lshlrev_b64 v[182:183], v198, v[182:183]
	v_lshlrev_b64 v[184:185], 10, v[184:185]
	v_lshl_add_u64 v[184:185], v[184:185], 0, v[182:183]
	v_lshl_add_u64 v[184:185], v[184:185], 0, v[186:187]
	v_lshlrev_b64 v[184:185], 2, v[184:185]
	v_cndmask_b32_e32 v183, v212, v213, vcc
	v_cndmask_b32_e32 v182, v214, v215, vcc
	v_lshl_add_u64 v[196:197], v[182:183], 0, v[184:185]
	v_cndmask_b32_e32 v183, v216, v217, vcc
	v_cndmask_b32_e32 v182, v218, v219, vcc
	v_lshl_add_u64 v[190:191], v[182:183], 0, v[184:185]
	global_load_dwordx4 v[64:67], v[194:195], off
	global_load_dwordx4 v[68:71], v[196:197], off
	global_load_dwordx4 v[72:75], v[194:195], off offset:64
	global_load_dwordx4 v[76:79], v[196:197], off offset:64
	global_load_dwordx4 v[80:83], v[194:195], off offset:128
	global_load_dwordx4 v[84:87], v[196:197], off offset:128
	global_load_dwordx4 v[88:91], v[194:195], off offset:192
	global_load_dwordx4 v[92:95], v[196:197], off offset:192
	v_add_u32_e32 v178, 48, v211
	v_mul_hi_i32 v179, v178, s97
	v_lshrrev_b32_e32 v180, 31, v179
	v_ashrrev_i32_e32 v179, 11, v179
	v_add_u32_e32 v179, v179, v180
	v_mul_i32_i24_e32 v180, 0x1100, v179
	v_sub_u32_e32 v180, v178, v180
	v_cmp_gt_i32_e32 vcc, s27, v180
	v_add_u32_e32 v181, s84, v179
	v_add_u32_e32 v198, 0xffffff00, v180
	v_ashrrev_i32_e32 v199, 31, v180
	v_cndmask_b32_e64 v179, v181, 8, vcc
	v_mul_hi_i32_i24_e32 v183, 0x3000, v179
	v_mul_i32_i24_e32 v182, 0x3000, v179
	v_lshl_add_u64 v[182:183], s[28:29], 0, v[182:183]
	v_lshl_add_u64 v[182:183], v[182:183], 0, s[0:1]
	v_lshl_add_u64 v[194:195], v[182:183], 0, v[188:189]
	v_cndmask_b32_e32 v185, 0, v199, vcc
	v_cndmask_b32_e32 v184, v198, v180, vcc
	v_mov_b32_e32 v182, v181
	v_ashrrev_i32_e32 v183, 31, v181
	v_cndmask_b32_e64 v198, 22, 18, vcc
	v_lshlrev_b64 v[182:183], v198, v[182:183]
	v_lshlrev_b64 v[184:185], 10, v[184:185]
	v_lshl_add_u64 v[184:185], v[184:185], 0, v[182:183]
	v_lshl_add_u64 v[184:185], v[184:185], 0, v[186:187]
	v_lshlrev_b64 v[184:185], 2, v[184:185]
	v_cndmask_b32_e32 v183, v212, v213, vcc
	v_cndmask_b32_e32 v182, v214, v215, vcc
	v_lshl_add_u64 v[196:197], v[182:183], 0, v[184:185]
	v_cndmask_b32_e32 v183, v216, v217, vcc
	v_cndmask_b32_e32 v182, v218, v219, vcc
	v_lshl_add_u64 v[192:193], v[182:183], 0, v[184:185]
	global_load_dwordx4 v[96:99], v[194:195], off
	global_load_dwordx4 v[100:103], v[196:197], off
	global_load_dwordx4 v[104:107], v[194:195], off offset:64
	global_load_dwordx4 v[108:111], v[196:197], off offset:64
	global_load_dwordx4 v[112:115], v[194:195], off offset:128
	global_load_dwordx4 v[116:119], v[196:197], off offset:128
	global_load_dwordx4 v[120:123], v[194:195], off offset:192
	global_load_dwordx4 v[124:127], v[196:197], off offset:192
	s_waitcnt vmcnt(0)
	v_pk_fma_f32 v[30:31], v[30:31], v[66:67], v[70:71]
	v_pk_fma_f32 v[28:29], v[28:29], v[64:65], v[68:69]
	global_store_dwordx4 v[190:191], v[28:31], off
	v_pk_fma_f32 v[26:27], v[26:27], v[74:75], v[78:79]
	v_pk_fma_f32 v[24:25], v[24:25], v[72:73], v[76:77]
	global_store_dwordx4 v[190:191], v[24:27], off offset:64
	v_pk_fma_f32 v[22:23], v[22:23], v[82:83], v[86:87]
	v_pk_fma_f32 v[20:21], v[20:21], v[80:81], v[84:85]
	global_store_dwordx4 v[190:191], v[20:23], off offset:128
	v_pk_fma_f32 v[18:19], v[18:19], v[90:91], v[94:95]
	v_pk_fma_f32 v[16:17], v[16:17], v[88:89], v[92:93]
	global_store_dwordx4 v[190:191], v[16:19], off offset:192
	v_pk_fma_f32 v[14:15], v[14:15], v[98:99], v[102:103]
	v_pk_fma_f32 v[12:13], v[12:13], v[96:97], v[100:101]
	global_store_dwordx4 v[192:193], v[12:15], off
	v_pk_fma_f32 v[10:11], v[10:11], v[106:107], v[110:111]
	v_pk_fma_f32 v[8:9], v[8:9], v[104:105], v[108:109]
	global_store_dwordx4 v[192:193], v[8:11], off offset:64
	v_pk_fma_f32 v[2:3], v[2:3], v[114:115], v[118:119]
	v_pk_fma_f32 v[0:1], v[0:1], v[112:113], v[116:117]
	global_store_dwordx4 v[192:193], v[0:3], off offset:128
	v_pk_fma_f32 v[6:7], v[6:7], v[122:123], v[126:127]
	v_pk_fma_f32 v[4:5], v[4:5], v[120:121], v[124:125]
	global_store_dwordx4 v[192:193], v[4:7], off offset:192
	s_andn2_b64 vcc, exec, s[22:23]
	s_cbranch_vccz .LBB0_556
